# g1 tail: next-FFN weight prep loop replaced by the hand-written tile loop (all loads in flight, prefetch), padded to keep code placement
# speedup vs baseline: 1.0092x; 1.0092x over previous
.LBB0_414:
	s_andn2_b64 vcc, exec, s[14:15]
	s_cbranch_vccnz .LBB0_432
	v_readlane_b32 s0, v252, 63
	v_readlane_b32 s1, v253, 0
	s_andn2_b64 vcc, exec, s[0:1]
	s_cbranch_vccnz .LBB0_432
	s_mov_b64 s[44:45], exec
	v_lshrrev_b32_e32 v0, 8, v141
	v_readlane_b32 s0, v253, 1
	v_readfirstlane_b32 s12, v0
	v_and_b32_e32 v8, 15, v141
	v_lshlrev_b32_e32 v8, 4, v8
	v_bfe_u32 v29, v141, 4, 4
	v_and_b32_e32 v20, 7, v141
	v_mul_u32_u24_e32 v1, 0x820, v20
	v_lshlrev_b32_e32 v20, 4, v20
	v_bfe_u32 v33, v141, 3, 5
	s_add_i32 s13, s0, s12
	s_lshl_b32 s0, s12, 16
	s_add_i32 s0, s0, 16
	v_mul_u32_u24_e32 v32, 0x104, v29
	v_add3_u32 v30, v8, v32, s0
	v_add_u32_e32 v47, 0x1040, v30
	v_add_u32_e32 v48, 0x2080, v30
	v_add_u32_e32 v49, 0x30c0, v30
	v_lshl_add_u32 v34, v33, 2, v1
	v_add_u32_e32 v34, s0, v34
	v_add_u32_e32 v35, 0x400, v34
	v_lshl_add_u32 v40, v29, 12, v8
	v_mad_u32_u24 v42, v29, s63, v8
	v_lshl_add_u32 v43, v33, 11, v20
	v_mov_b32_e32 v0, 0x1600
	v_mad_u32_u24 v44, v33, v0, v20
	v_lshlrev_b32_e32 v45, 2, v29
	s_mov_b32 s12, 0
	s_mov_b32 s14, 0
	s_waitcnt lgkmcnt(0)

.Lpt_pf:
	s_cmpk_ge_u32 s13, 0x840
	s_cbranch_scc1 .Lpt_s2
	s_cmpk_ge_u32 s13, 0x580
	s_cbranch_scc1 .Lpt_twd
	s_sub_u32 s0, s13, 0x2c0
	v_readlane_b32 s40, v252, 16
	v_readlane_b32 s41, v252, 17
	v_readlane_b32 s48, v252, 18
	v_readlane_b32 s49, v252, 19
	s_cmp_lt_u32 s0, s62
	s_cselect_b32 s15, 1, 0
	s_cselect_b32 s1, s0, s13
	s_cselect_b64 s[40:41], s[48:49], s[40:41]
	s_add_u32 s40, s40, s92
	s_addc_u32 s41, s41, 0
	s_and_b32 s0, s1, 15
	s_lshr_b32 s1, s1, 4
	s_lshl_b32 s19, s1, 8
	s_mul_i32 s18, s0, s63
	s_lshl_b32 s18, s18, 6
	s_add_u32 s18, s18, s19
	s_add_u32 s40, s40, s18
	s_addc_u32 s41, s41, 0
	s_lshl_b32 s4, s63, 4
	s_lshl_b32 s18, s0, 8
	s_add_u32 s46, s8, s18
	s_addc_u32 s47, s9, 0
	s_lshr_b32 s18, s1, 1
	s_lshl_b32 s18, s18, 8
	s_and_b32 s19, s1, 1
	s_lshl_b32 s19, s19, 6
	s_add_u32 s18, s18, s19
	s_lshl_b32 s19, s15, 7
	s_add_u32 s18, s18, s19
	s_lshl_b32 s18, s18, 11
	s_lshl_b32 s19, s0, 7
	s_add_u32 s18, s18, s19
	s_add_u32 s48, s42, s18
	s_addc_u32 s49, s43, 0
	s_add_u32 s50, s48, 0x10000
	s_addc_u32 s51, s49, 0
	s_mov_b32 s18, 1
	s_and_b64 s[0:1], s[60:61], exec
	s_cselect_b32 s19, 1, 0
	v_mov_b32_e32 v50, v42
	v_mov_b32_e32 v51, v43
	s_branch .Lpt_issue
.Lpt_twd:
	s_sub_u32 s0, s13, 0x580
	s_mul_hi_u32 s1, s0, 0xba2e8ba3
	s_lshr_b32 s1, s1, 5
	s_mul_i32 s15, s1, 44
	s_sub_u32 s0, s0, s15
	v_readlane_b32 s40, v252, 20
	v_readlane_b32 s41, v252, 21
	s_add_u32 s40, s40, s92
	s_addc_u32 s41, s41, 0
	s_lshl_b32 s15, s1, 8
	s_lshl_b32 s19, s0, 18
	s_add_u32 s15, s15, s19
	s_add_u32 s40, s40, s15
	s_addc_u32 s41, s41, 0
	s_mov_b32 s4, 0x10000
	s_mov_b32 s18, 0
	s_mul_i32 s15, s1, 0x58000
	s_lshl_b32 s19, s0, 7
	s_add_u32 s15, s15, s19
	s_add_u32 s48, s30, s15
	s_addc_u32 s49, s31, 0
	s_add_u32 s50, s48, 0x2c000
	s_addc_u32 s51, s49, 0
	v_mov_b32_e32 v50, v40
	v_mov_b32_e32 v51, v44
.Lpt_issue:
	global_load_dwordx4 v[52:55], v50, s[40:41]
	s_add_u32 s40, s40, s4
	s_addc_u32 s41, s41, 0
	global_load_dwordx4 v[56:59], v50, s[40:41]
	s_add_u32 s40, s40, s4
	s_addc_u32 s41, s41, 0
	global_load_dwordx4 v[60:63], v50, s[40:41]
	s_add_u32 s40, s40, s4
	s_addc_u32 s41, s41, 0
	global_load_dwordx4 v[64:67], v50, s[40:41]
	s_cmp_eq_u32 s18, 0
	s_cbranch_scc1 .Lpt_s2
	v_mov_b32_e32 v68, 1.0
	v_mov_b32_e32 v70, 1.0
	v_mov_b32_e32 v72, 1.0
	v_mov_b32_e32 v74, 1.0
	s_cmp_eq_u32 s19, 0
	s_cbranch_scc1 .Lpt_s2
	global_load_dword v68, v45, s[46:47]
	global_load_dword v70, v45, s[46:47] offset:64
	global_load_dword v72, v45, s[46:47] offset:128
	global_load_dword v74, v45, s[46:47] offset:192

.Lpt_rot:
	s_cmpk_ge_u32 s13, 0x840
	s_cbranch_scc1 .Lpt_done
	s_mov_b64 s[36:37], s[48:49]
	s_mov_b64 s[38:39], s[50:51]
	v_mov_b32_e32 v46, v51
	s_mov_b32 s14, s18
	s_add_i32 s12, s12, 1
	s_min_u32 s12, s12, 2
	s_addk_i32 s13, 0x100
	s_branch .Lpt_loop
	s_nop 0
	s_nop 0
	s_nop 0
	s_nop 0
	s_nop 0
	s_nop 0
	s_nop 0
	s_nop 0
	s_nop 0
	s_nop 0
	s_nop 0
	s_nop 0
	s_nop 0
	s_nop 0
	s_nop 0
	s_nop 0
	s_nop 0
	s_nop 0
	s_nop 0
	s_nop 0
	s_nop 0
	s_nop 0
	s_nop 0
	s_nop 0
	s_nop 0
	s_nop 0
	s_nop 0
	s_nop 0
	s_nop 0
	s_nop 0
	s_nop 0
	s_nop 0
	s_nop 0
	s_nop 0
	s_nop 0
	s_nop 0
	s_nop 0
	s_nop 0
	s_nop 0
	s_nop 0
	s_nop 0
	s_nop 0
	s_nop 0
	s_nop 0
	s_nop 0
	s_nop 0
	s_nop 0
	s_nop 0
	s_nop 0
	s_nop 0
	s_nop 0
	s_nop 0
	s_nop 0
	s_nop 0
	s_nop 0
	s_nop 0
	s_nop 0
	s_nop 0
	s_nop 0
	s_nop 0
	s_nop 0
	s_nop 0
	s_nop 0
	s_nop 0
	s_nop 0
	s_nop 0
	s_nop 0
	s_nop 0
	s_nop 0
	s_nop 0
	s_nop 0
	s_nop 0
	s_nop 0
	s_nop 0
	s_nop 0
	s_nop 0
	s_nop 0
	s_nop 0
	s_nop 0
	s_nop 0
	s_nop 0
	s_nop 0
	s_nop 0
	s_nop 0
	s_nop 0
	s_nop 0
	s_nop 0
	s_nop 0
	s_nop 0
	s_nop 0
	s_nop 0
	s_nop 0
	s_nop 0
	s_nop 0
	s_nop 0
	s_nop 0
	s_nop 0
	s_nop 0
	s_nop 0
	s_nop 0
	s_nop 0
	s_nop 0
	s_nop 0
	s_nop 0
	s_nop 0
	s_nop 0
	s_nop 0
	s_nop 0
	s_nop 0
	s_nop 0
	s_nop 0
	s_nop 0
	s_nop 0
	s_nop 0
	s_nop 0
	s_nop 0
	s_nop 0
	s_nop 0
	s_nop 0
	s_nop 0
	s_nop 0
	s_nop 0
	s_nop 0
	s_nop 0
	s_nop 0
	s_nop 0
	s_nop 0
	s_nop 0
	s_nop 0
	s_nop 0
	s_nop 0
	s_nop 0
	s_nop 0
	s_nop 0
	s_nop 0
	s_nop 0
	s_nop 0
	s_nop 0
	s_nop 0
	s_nop 0
	s_nop 0
	s_nop 0
	s_nop 0
	s_nop 0
	s_nop 0
	s_nop 0
	s_nop 0
	s_nop 0
	s_nop 0
	s_nop 0
	s_nop 0
	s_nop 0
	s_nop 0
	s_nop 0
	s_nop 0
	s_nop 0
	s_nop 0
	s_nop 0
	s_nop 0
	s_nop 0
	s_nop 0
	s_nop 0
	s_nop 0
	s_nop 0
	s_nop 0
	s_nop 0
	s_nop 0
	s_nop 0
	s_nop 0
	s_nop 0
	s_nop 0
	s_nop 0
	s_nop 0
	s_nop 0
	s_nop 0
	s_nop 0
